# k11 plus one static s_setprio 1 for waves 4-7 during the mixer-A attention units (reset afterwards)
# speedup vs baseline: 1.0040x; 1.0035x over previous
; __device__ __forceinline__ unsigned cvt_pk_bf16(float lo, float hi) { unsigned r; asm("v_cvt_pk_bf16_f32 %0, %1, %2" : "=v"(r) : "v"(lo), "v"(hi)); return r; }
; __device__ __forceinline__ float bflo(unsigned w) { return __uint_as_float(w << 16); }
; __device__ __forceinline__ float bfhi(unsigned w) { return __uint_as_float(w & 0xffff0000u); }
; __device__ __forceinline__ size_t pbh(int seg, int b, int cb) { return ((size_t)((seg * 16 + b) * 8 + cb) * SEQ) * 128; }
; __device__ __forceinline__ void attn_b2_unit(int b, int h, int qk, int jlo, const bf16_t* __restrict__ P, bf16_t* __restrict__ mix, const float* __restrict__ subg, float lam,
;                                              float* __restrict__ o0s, char* lds) {
;     ...
;             for (int i = 0; i < 8; ++i) { const int id = i * 512 + tid3, row = id >> 5, c16 = id & 31;
;                 const u32x4 v = *(const u32x4*)(lds + row * B2_STG_PITCH + c16 * 16);
;                 const int col = h * 256 + c16 * 8;
;                 const u32x4 gt = *(const u32x4*)(P + pbh(7, b, 2 * h + (c16 >> 4)) + (size_t)(128 * qk + row) * 128 + (c16 & 15) * 8);
;                 const f32x4 g0 = *(const f32x4*)(subg + c16 * 8), g1 = *(const f32x4*)(subg + c16 * 8 + 4);
;                 u32x4 w;
;                 w.x = cvt_pk_bf16(bflo(v.x) * g0[0] * bflo(gt.x), bfhi(v.x) * g0[1] * bfhi(gt.x));
;                 w.y = cvt_pk_bf16(bflo(v.y) * g0[2] * bflo(gt.y), bfhi(v.y) * g0[3] * bfhi(gt.y));
;                 w.z = cvt_pk_bf16(bflo(v.z) * g1[0] * bflo(gt.z), bfhi(v.z) * g1[1] * bfhi(gt.z));
;                 w.w = cvt_pk_bf16(bflo(v.w) * g1[2] * bflo(gt.w), bfhi(v.w) * g1[3] * bfhi(gt.w));
;                 *(u32x4*)(mix + (rowb + 128 * qk + row) * DM + 1024 + col) = w; }
.LBB0_401:
	v_add_u32_e32 v11, s30, v1
	v_ashrrev_i32_e32 v20, 5, v11
	v_add_u32_e32 v18, 0x200, v11
	v_add_u32_e32 v19, 0x400, v11
	v_add_u32_e32 v11, 0x600, v11
	v_add_u32_e32 v22, s74, v20
	v_ashrrev_i32_e32 v21, 31, v20
	v_ashrrev_i32_e32 v24, 5, v18
	v_ashrrev_i32_e32 v28, 5, v19
	v_ashrrev_i32_e32 v32, 5, v11
	v_ashrrev_i32_e32 v23, 31, v22
	v_mad_u64_u32 v[16:17], s[2:3], v20, s1, v[10:11]
	v_lshl_add_u64 v[20:21], s[38:39], 0, v[20:21]
	v_mad_u64_u32 v[26:27], s[2:3], v24, s1, v[10:11]
	v_add_u32_e32 v34, s74, v24
	v_ashrrev_i32_e32 v25, 31, v24
	v_mad_u64_u32 v[30:31], s[2:3], v28, s1, v[10:11]
	v_ashrrev_i32_e32 v29, 31, v28
	v_mad_u64_u32 v[38:39], s[2:3], v32, s1, v[10:11]
	v_ashrrev_i32_e32 v33, 31, v32
	v_lshlrev_b64 v[42:43], 8, v[22:23]
	ds_read_b128 v[16:19], v16
	v_add_u32_e32 v36, s74, v28
	v_add_u32_e32 v40, s74, v32
	v_lshlrev_b64 v[44:45], 12, v[20:21]
	ds_read_b128 v[20:23], v26
	v_ashrrev_i32_e32 v35, 31, v34
	v_lshl_add_u64 v[46:47], s[38:39], 0, v[24:25]
	ds_read_b128 v[24:27], v30
	v_lshl_add_u64 v[48:49], s[38:39], 0, v[28:29]
	ds_read_b128 v[28:31], v38
	v_lshl_add_u64 v[32:33], s[38:39], 0, v[32:33]
	v_lshl_add_u64 v[38:39], v[12:13], 0, v[42:43]
	v_ashrrev_i32_e32 v37, 31, v36
	v_ashrrev_i32_e32 v41, 31, v40
	v_lshl_add_u64 v[50:51], v[14:15], 0, v[44:45]
	v_lshlrev_b64 v[42:43], 8, v[34:35]
	v_lshlrev_b64 v[44:45], 12, v[46:47]
	v_lshlrev_b64 v[46:47], 12, v[48:49]
	v_lshlrev_b64 v[48:49], 12, v[32:33]
	global_load_dwordx4 v[32:35], v[38:39], off
	v_lshlrev_b64 v[36:37], 8, v[36:37]
	v_lshlrev_b64 v[40:41], 8, v[40:41]
	v_lshl_add_u64 v[38:39], v[12:13], 0, v[42:43]
	v_lshl_add_u64 v[52:53], v[14:15], 0, v[44:45]
	v_lshl_add_u64 v[42:43], v[12:13], 0, v[36:37]
	v_lshl_add_u64 v[44:45], v[12:13], 0, v[40:41]
	v_lshl_add_u64 v[54:55], v[14:15], 0, v[46:47]
	global_load_dwordx4 v[36:39], v[38:39], off
	s_nop 0
	global_load_dwordx4 v[40:43], v[42:43], off
	s_nop 0
	global_load_dwordx4 v[44:47], v[44:45], off
	s_waitcnt lgkmcnt(0)
	v_lshlrev_b32_e32 v11, 16, v16
	v_and_b32_e32 v16, 0xffff0000, v16
	v_lshlrev_b32_e32 v56, 16, v17
	v_and_b32_e32 v17, 0xffff0000, v17
	v_lshlrev_b32_e32 v57, 16, v18
	v_and_b32_e32 v18, 0xffff0000, v18
	v_lshlrev_b32_e32 v58, 16, v19
	v_and_b32_e32 v19, 0xffff0000, v19
	s_waitcnt vmcnt(0)
	v_mul_f32_e32 v16, v3, v16
	v_mul_f32_e32 v17, v5, v17
	v_mul_f32_e32 v18, v7, v18
	v_mul_f32_e32 v19, v9, v19
	v_mul_f32_e32 v11, v2, v11
	v_mul_f32_e32 v56, v4, v56
	v_mul_f32_e32 v57, v6, v57
	v_mul_f32_e32 v58, v8, v58
	v_lshlrev_b32_e32 v59, 16, v20
	v_and_b32_e32 v20, 0xffff0000, v20
	v_lshlrev_b32_e32 v60, 16, v21
	v_and_b32_e32 v21, 0xffff0000, v21
	v_lshlrev_b32_e32 v61, 16, v22
	v_and_b32_e32 v22, 0xffff0000, v22
	v_lshlrev_b32_e32 v62, 16, v23
	v_and_b32_e32 v23, 0xffff0000, v23
	v_lshlrev_b32_e32 v63, 16, v24
	v_and_b32_e32 v24, 0xffff0000, v24
	v_lshlrev_b32_e32 v64, 16, v25
	v_and_b32_e32 v25, 0xffff0000, v25
	v_lshlrev_b32_e32 v65, 16, v26
	v_and_b32_e32 v26, 0xffff0000, v26
	v_lshlrev_b32_e32 v66, 16, v27
	v_and_b32_e32 v27, 0xffff0000, v27
	s_addk_i32 s30, 0x800
	v_lshlrev_b32_e32 v67, 16, v28
	v_and_b32_e32 v28, 0xffff0000, v28
	v_lshlrev_b32_e32 v68, 16, v29
	v_and_b32_e32 v29, 0xffff0000, v29
	v_lshlrev_b32_e32 v69, 16, v30
	v_and_b32_e32 v30, 0xffff0000, v30
	v_lshlrev_b32_e32 v70, 16, v31
	v_and_b32_e32 v31, 0xffff0000, v31
	v_mul_f32_e32 v59, v2, v59
	v_mul_f32_e32 v20, v3, v20
	v_mul_f32_e32 v60, v4, v60
	v_mul_f32_e32 v21, v5, v21
	v_mul_f32_e32 v61, v6, v61
	v_mul_f32_e32 v22, v7, v22
	v_mul_f32_e32 v62, v8, v62
	v_mul_f32_e32 v23, v9, v23
	v_mul_f32_e32 v24, v3, v24
	v_mul_f32_e32 v25, v5, v25
	v_mul_f32_e32 v26, v7, v26
	v_mul_f32_e32 v27, v9, v27
	s_cmpk_eq_i32 s30, 0x1000
	v_mul_f32_e32 v63, v2, v63
	v_mul_f32_e32 v64, v4, v64
	v_mul_f32_e32 v65, v6, v65
	v_mul_f32_e32 v66, v8, v66
	v_mul_f32_e32 v67, v2, v67
	v_mul_f32_e32 v28, v3, v28
	v_mul_f32_e32 v68, v4, v68
	v_mul_f32_e32 v29, v5, v29
	v_mul_f32_e32 v69, v6, v69
	v_mul_f32_e32 v30, v7, v30
	v_mul_f32_e32 v70, v8, v70
	v_mul_f32_e32 v31, v9, v31
	v_lshl_add_u64 v[48:49], v[14:15], 0, v[48:49]
	v_lshlrev_b32_e32 v71, 16, v32
	v_and_b32_e32 v32, 0xffff0000, v32
	v_lshlrev_b32_e32 v72, 16, v33
	v_and_b32_e32 v33, 0xffff0000, v33
	v_lshlrev_b32_e32 v73, 16, v34
	v_and_b32_e32 v34, 0xffff0000, v34
	v_lshlrev_b32_e32 v74, 16, v35
	v_and_b32_e32 v35, 0xffff0000, v35
	v_mul_f32_e32 v16, v16, v32
	v_mul_f32_e32 v17, v17, v33
	v_mul_f32_e32 v18, v18, v34
	v_mul_f32_e32 v19, v19, v35
	v_mul_f32_e32 v11, v11, v71
	v_mul_f32_e32 v32, v56, v72
	v_mul_f32_e32 v33, v57, v73
	v_mul_f32_e32 v34, v58, v74
	v_lshlrev_b32_e32 v35, 16, v36
	v_and_b32_e32 v36, 0xffff0000, v36
	v_lshlrev_b32_e32 v56, 16, v37
	v_and_b32_e32 v37, 0xffff0000, v37
	v_lshlrev_b32_e32 v57, 16, v38
	v_and_b32_e32 v38, 0xffff0000, v38
	v_lshlrev_b32_e32 v58, 16, v39
	v_and_b32_e32 v39, 0xffff0000, v39
	v_lshlrev_b32_e32 v71, 16, v40
	v_and_b32_e32 v40, 0xffff0000, v40
	v_lshlrev_b32_e32 v72, 16, v41
	v_and_b32_e32 v41, 0xffff0000, v41
	v_lshlrev_b32_e32 v73, 16, v42
	v_and_b32_e32 v42, 0xffff0000, v42
	v_lshlrev_b32_e32 v74, 16, v43
	v_and_b32_e32 v43, 0xffff0000, v43
	v_cvt_pk_bf16_f32 v16, v11, v16
	v_cvt_pk_bf16_f32 v17, v32, v17
	v_cvt_pk_bf16_f32 v18, v33, v18
	v_cvt_pk_bf16_f32 v19, v34, v19
	v_lshlrev_b32_e32 v75, 16, v44
	v_and_b32_e32 v44, 0xffff0000, v44
	v_lshlrev_b32_e32 v76, 16, v45
	v_and_b32_e32 v45, 0xffff0000, v45
	v_lshlrev_b32_e32 v77, 16, v46
	v_and_b32_e32 v46, 0xffff0000, v46
	v_lshlrev_b32_e32 v78, 16, v47
	v_and_b32_e32 v47, 0xffff0000, v47
	v_mul_f32_e32 v11, v59, v35
	v_mul_f32_e32 v20, v20, v36
	v_mul_f32_e32 v32, v60, v56
	v_mul_f32_e32 v21, v21, v37
	v_mul_f32_e32 v33, v61, v57
	v_mul_f32_e32 v22, v22, v38
	v_mul_f32_e32 v34, v62, v58
	v_mul_f32_e32 v23, v23, v39
	v_mul_f32_e32 v24, v24, v40
	v_mul_f32_e32 v25, v25, v41
	v_mul_f32_e32 v26, v26, v42
	v_mul_f32_e32 v27, v27, v43
	global_store_dwordx4 v[50:51], v[16:19], off offset:2048
	v_mul_f32_e32 v35, v63, v71
	v_mul_f32_e32 v36, v64, v72
	v_cvt_pk_bf16_f32 v16, v11, v20
	v_cvt_pk_bf16_f32 v17, v32, v21
	v_cvt_pk_bf16_f32 v18, v33, v22
	v_cvt_pk_bf16_f32 v19, v34, v23
	v_mul_f32_e32 v37, v65, v73
	v_mul_f32_e32 v38, v66, v74
	v_mul_f32_e32 v39, v67, v75
	v_mul_f32_e32 v28, v28, v44
	v_mul_f32_e32 v40, v68, v76
	v_mul_f32_e32 v29, v29, v45
	v_mul_f32_e32 v41, v69, v77
	v_mul_f32_e32 v30, v30, v46
	v_mul_f32_e32 v42, v70, v78
	v_mul_f32_e32 v31, v31, v47
	v_cvt_pk_bf16_f32 v20, v35, v24
	v_cvt_pk_bf16_f32 v21, v36, v25
	v_cvt_pk_bf16_f32 v22, v37, v26
	v_cvt_pk_bf16_f32 v23, v38, v27
	v_cvt_pk_bf16_f32 v24, v39, v28
	v_cvt_pk_bf16_f32 v25, v40, v29
	v_cvt_pk_bf16_f32 v26, v41, v30
	v_cvt_pk_bf16_f32 v27, v42, v31
	global_store_dwordx4 v[52:53], v[16:19], off offset:2048
	global_store_dwordx4 v[54:55], v[20:23], off offset:2048
	global_store_dwordx4 v[48:49], v[24:27], off offset:2048
	s_cbranch_scc0 .LBB0_401
; __global__ void __launch_bounds__(512, 2) mega(Params p) {
;     ...
;         for (int L = bid; L < 1024; L += G) {
;             int b_, h_, qk;
;             if (G == 256) {
;                 const int k4 = (L / G) & 3, xcd = bid & 7, li = bid >> 3, i16 = li & 15;
;                 b_ = xcd * 2 + (li >> 4); h_ = (k4 + 2) & 3;
;                 qk = k4 == 0 ? 15 - i16 : (k4 == 1 ? i16 : (k4 == 2 ? 15 - ((i16 + 8) & 15) : ((i16 + 8) & 15)));
;             } else { b_ = L >> 6; h_ = (L >> 4) & 3; qk = 15 - (L & 15); }
;             const float dist = (2.f * smax + 25.f) * exp2f(2.f * (float)(h_ + 1));
;             const int jlo = max(0, (int)ceilf((128.f * (float)qk - 63.f - dist) * (1.f / 64.f)));
;             attn_b2_unit(b_, h_, qk, jlo, PB, MIX, p.in[I_SUBG], lam, (float*)(ws + WS_O0), ldsg);
;         }
;         for (int ra_ = 0; ra_ <= DUPA; ++ra_)
;         for (int L = bid; L < 1024; L += G) {
;             const int qb = L >> 7, bh = L & 127;
;             attn_a_unit(bh >> 3, bh & 7, qb, PB, MIX, p.in[I_RELB], ldsg);
	s_waitcnt lgkmcnt(0)
	s_and_b64 vcc, exec, s[42:43]
	s_mov_b64 s[42:43], 0
	s_mov_b64 s[40:41], -1
	s_cbranch_vccz .LBB0_340
	s_add_i32 s56, s56, s88
	s_cmpk_gt_i32 s56, 0x3ff
	s_cbranch_scc0 .LBB0_325
	v_readfirstlane_b32 s0, v188
	s_nop 3
	s_lshr_b32 s0, s0, 6
	s_cmp_ge_u32 s0, 4
	s_cbranch_scc0 .Lprio_a_skip
	s_setprio 1
.Lprio_a_skip:
	v_and_b32_e32 v0, 63, v188
	v_cmp_gt_u32_e64 s[6:7], 32, v0
	v_bfe_u32 v0, v188, 5, 1
	v_lshlrev_b32_e32 v149, 4, v0
	v_mul_u32_u24_e32 v151, 0x440, v0
	v_lshlrev_b32_e32 v0, 3, v188
	s_movk_i32 s0, 0x101
	v_and_b32_e32 v2, 0x78, v0
	v_cmp_gt_u32_e64 s[4:5], s0, v188
	s_add_i32 s0, 0, 0x11000
	v_mov_b32_e32 v1, 0
	v_bfe_u32 v144, v188, 4, 2
	v_lshlrev_b32_e32 v0, 1, v2
	v_and_b32_e32 v145, 31, v188
	s_mov_b32 s17, 0
	v_lshl_add_u32 v147, v188, 2, s0
	v_mul_u32_u24_e32 v153, 0x110, v144
	v_or_b32_e32 v146, 4, v144
	v_or_b32_e32 v148, 8, v144
	v_or_b32_e32 v150, 12, v144
	v_or_b32_e32 v152, 16, v144
	v_or_b32_e32 v154, 20, v144
	v_or_b32_e32 v156, 24, v144
	v_or_b32_e32 v158, 28, v144
	v_lshl_add_u64 v[160:161], s[14:15], 0, v[0:1]
	s_movk_i32 s1, 0x70
	s_movk_i32 s28, 0xf0
	s_movk_i32 s29, 0xc0
	s_movk_i32 s33, 0x60
	s_movk_i32 s34, 0x80
	s_movk_i32 s35, 0xa0
	s_movk_i32 s42, 0xe0
	s_movk_i32 s43, 0x118
	s_mov_b64 s[14:15], 0x107e4000
	s_mov_b64 s[18:19], 0x147e4000
	s_movk_i32 s44, 0xff80
	s_movk_i32 s45, 0xff60
	s_mov_b32 s48, 0x41000000
	v_lshlrev_b32_e32 v162, 1, v2
	s_mov_b64 s[20:21], 0xc000000
	v_mov_b32_e32 v155, 0x80
	v_mov_b32_e32 v157, 0x60
	s_mov_b32 s49, s84
	s_mov_b32 s50, s84
	s_branch .LBB0_406

; __device__ __forceinline__ unsigned xb_ld(unsigned* p)              { return __hip_atomic_load(p, __ATOMIC_RELAXED, __HIP_MEMORY_SCOPE_AGENT); }
; __device__ __forceinline__ void xcd_barrier_complete(unsigned* bar, unsigned x, unsigned& nloc, unsigned& nx) {
;     const unsigned G = gridDim.x * gridDim.y * gridDim.z;
;     unsigned sum, cnt, mine, sp = 0u;
;     for (;;) {
;         sum = 0u; cnt = 0u; mine = 0u;
; #pragma unroll
;         for (unsigned j = 0; j < 16; ++j) { const unsigned c = xb_ld(&bar[XB_XCNT(j)]); sum += c; cnt += (c > 0u) ? 1u : 0u; mine = (j == x) ? c : mine; }
;         if (sum == G) break;
; __device__ __forceinline__ void xcd_barrier(const XcdBarrier& b) {
;     asm volatile("s_waitcnt vmcnt(0)" ::: "memory");
;     __syncthreads();
;     if (threadIdx.x == 0) {
;         unsigned* bar = b.bar;
;         __builtin_amdgcn_s_waitcnt(0);
;         unsigned nloc = b.st[0], nx = b.st[1];
;         if (nloc == 0u) { xcd_barrier_complete(bar, b.x, nloc, nx); b.st[0] = nloc; b.st[1] = nx; }
.LBB0_428:
	s_setprio 0
	s_waitcnt vmcnt(0)
	s_barrier
	s_mov_b64 s[0:1], exec
	v_readlane_b32 s2, v242, 9
	v_readlane_b32 s3, v242, 10
	s_and_b64 s[2:3], s[0:1], s[2:3]
	s_xor_b64 s[4:5], s[2:3], s[0:1]
	s_mov_b64 exec, s[2:3]
	s_cbranch_execz .LBB0_481
	s_add_i32 s0, 0, 0x23fc0
	v_mov_b32_e32 v0, s0
	s_waitcnt vmcnt(0) expcnt(0) lgkmcnt(0)
	ds_read_b32 v2, v0
	s_add_i32 s0, 0, 0x23fc4
	v_mov_b32_e32 v0, s0
	ds_read_b32 v0, v0
	s_waitcnt lgkmcnt(1)
	v_cmp_ne_u32_e32 vcc, 0, v2
	s_cbranch_vccnz .LBB0_444
	v_readlane_b32 s16, v242, 0
	v_readlane_b32 s22, v242, 6
	v_readlane_b32 s23, v242, 7
	s_add_u32 s6, s22, 0x50200
	s_addc_u32 s7, s23, 0
	s_add_u32 s8, s22, 0x50400
	s_addc_u32 s9, s23, 0
	s_add_u32 s10, s22, 0x50500
	s_addc_u32 s11, s23, 0
	s_add_u32 s12, s22, 0x50600
	s_addc_u32 s13, s23, 0
	s_add_u32 s14, s22, 0x50700
	s_addc_u32 s15, s23, 0
	v_readlane_b32 s17, v242, 1
	s_add_u32 s16, s22, 0x50800
	v_readlane_b32 s18, v242, 2
	s_addc_u32 s17, s23, 0
	v_readlane_b32 s19, v242, 3
	s_add_u32 s18, s22, 0x50900
	v_readlane_b32 s20, v242, 4
	s_addc_u32 s19, s23, 0
	v_readlane_b32 s21, v242, 5
	s_add_u32 s20, s22, 0x50a00
	s_addc_u32 s21, s23, 0
	s_add_u32 s24, s22, 0x50b00
	s_addc_u32 s25, s23, 0
	s_add_u32 s26, s22, 0x50c00
	s_addc_u32 s27, s23, 0
	s_add_u32 s36, s22, 0x50d00
	s_addc_u32 s37, s23, 0
	s_add_u32 s38, s22, 0x50e00
	s_addc_u32 s39, s23, 0
	s_add_u32 s40, s22, 0x50f00
	s_addc_u32 s41, s23, 0
	s_add_u32 s42, s22, 0x51000
	s_addc_u32 s43, s23, 0
	s_add_u32 s44, s22, 0x51100
	s_addc_u32 s45, s23, 0
	s_add_u32 s48, s22, 0x51200
	v_readlane_b32 s0, v242, 8
	s_addc_u32 s49, s23, 0
	s_mul_i32 s0, s89, s0
	s_add_u32 s50, s22, 0x51300
	s_mul_i32 s0, s0, s88
	s_addc_u32 s51, s23, 0
	s_mov_b32 s1, 1
	v_mov_b32_e32 v16, 0
	s_branch .LBB0_432
